# plus small latency fixes: ssd_pass2 state-tile loads batched, c1/c2 column-sum loads batched, ret_pass1 row prefetch
# speedup vs baseline: 1.0175x; 1.0117x over previous
; #define LAS __attribute__((address_space(3)))
; template <int MODE>
; DI void ret_stage(const Args& a, int row0, int h, float lg, LAS bf16_t* Qs, LAS bf16_t* Ks, LAS bf16_t* VT, LAS bf16_t* KT, int tid) {
;     const bf16_t* Hg = (const bf16_t*)(a.ws + WS_H); const float* tab = (const float*)(a.ws + WS_ROPE64);
;     const int t = tid >> 2, part = tid & 3, row = row0 + t; const bf16_t* hr = Hg + (size_t)row * HP;
;     float cs[16]; { const f32x4* tp = (const f32x4*)(tab + (size_t)row * 64 + part * 16);
; #pragma unroll
;         for (int i = 0; i < 4; ++i) { const f32x4 v = tp[i]; cs[4 * i] = v[0]; cs[4 * i + 1] = v[1]; cs[4 * i + 2] = v[2]; cs[4 * i + 3] = v[3]; } }
;     { float k1[8], k2[8], o1[8], o2[8]; unpack8(*(const u32x4*)(hr + C_RK + h * 64 + part * 8), k1); unpack8(*(const u32x4*)(hr + C_RK + h * 64 + 32 + part * 8), k2);
;       const float sc = 0.125f * (MODE == 0 ? __expf(lg * (float)(127 - t)) : 1.0f);
; #pragma unroll
;       for (int i = 0; i < 8; ++i) { o1[i] = (k1[i] * cs[2 * i] - k2[i] * cs[2 * i + 1]) * sc; o2[i] = (k1[i] * cs[2 * i + 1] + k2[i] * cs[2 * i]) * sc; }
;       if (MODE == 0) {
; #pragma unroll
;           for (int i = 0; i < 8; ++i) { KT[(part * 8 + i) * PT + t] = f2bf(o1[i]); KT[(32 + part * 8 + i) * PT + t] = f2bf(o2[i]); } }
;       else { *(LAS u32x4*)(Ks + t * PQ + part * 8) = pack8(o1); *(LAS u32x4*)(Ks + t * PQ + 32 + part * 8) = pack8(o2); } }
;     if (MODE == 1) { float q1[8], q2[8], o1[8], o2[8]; unpack8(*(const u32x4*)(hr + C_RQ + h * 64 + part * 8), q1); unpack8(*(const u32x4*)(hr + C_RQ + h * 64 + 32 + part * 8), q2);
; #pragma unroll
;       for (int i = 0; i < 8; ++i) { o1[i] = q1[i] * cs[2 * i] - q2[i] * cs[2 * i + 1]; o2[i] = q1[i] * cs[2 * i + 1] + q2[i] * cs[2 * i]; }
;       *(LAS u32x4*)(Qs + t * PQ + part * 8) = pack8(o1); *(LAS u32x4*)(Qs + t * PQ + 32 + part * 8) = pack8(o2); }
;     { float v[8]; unpack8(*(const u32x4*)(hr + C_RV + h * 64 + part * 16), v);
; #pragma unroll
;       for (int i = 0; i < 8; ++i) VT[(part * 16 + i) * PT + t] = f2bf(v[i]);
;       unpack8(*(const u32x4*)(hr + C_RV + h * 64 + part * 16 + 8), v);
; #pragma unroll
;       for (int i = 0; i < 8; ++i) VT[(part * 16 + 8 + i) * PT + t] = f2bf(v[i]); }
; DI void ret_pass1(LAS unsigned char* lds, const Args& a, int unit, int wv) {
;     const int wave = wv, c = unit & (NCH - 1), b = unit >> 7, row0 = b * SEQ + c * 128;
.LBB0_998:
	s_mov_b32 s13, s77
	v_mbcnt_lo_u32_b32 v34, -1, 0
	v_mbcnt_hi_u32_b32 v34, -1, v34
	v_mov_b32_e32 v7, v1
	v_lshl_or_b32 v0, s13, 6, v34
	v_ashrrev_i32_e32 v40, 2, v0
	v_lshl_add_u32 v2, s7, 7, v40
	v_ashrrev_i32_e32 v3, 31, v2
	v_and_b32_e32 v28, 3, v34
	v_lshlrev_b64 v[4:5], 8, v[2:3]
	v_lshl_add_u64 v[4:5], s[16:17], 0, v[4:5]
	v_lshlrev_b32_e32 v6, 6, v28
	v_lshl_add_u64 v[14:15], v[4:5], 0, v[6:7]
	v_mov_b64_e32 v[4:5], s[18:19]
	v_mad_i64_i32 v[18:19], s[14:15], v2, s73, v[4:5]
	v_sub_u32_e32 v2, 0x7f, v40
	v_cvt_f32_i32_e32 v39, v2
	v_lshlrev_b32_e32 v2, 5, v28
	v_mov_b32_e32 v3, v1
	v_lshl_add_u64 v[26:27], v[18:19], 0, v[2:3]
	s_mov_b64 s[14:15], 0xf20
	v_lshl_add_u64 v[22:23], v[26:27], 0, s[14:15]
	v_mov_b32_e32 v2, 0x110
	s_movk_i32 s14, 0x1100
	v_mad_u32_u24 v37, v28, s14, v2
	v_mov_b32_e32 v2, 0x220
	v_mad_u32_u24 v35, v28, s14, v2
	v_mov_b32_e32 v2, 0x330
	v_mad_u32_u24 v33, v28, s14, v2
	v_mov_b32_e32 v2, 0x440
	v_mad_u32_u24 v32, v28, s14, v2
	v_mov_b32_e32 v2, 0x550
	v_lshlrev_b32_e32 v0, 4, v28
	v_mad_u32_u24 v31, v28, s14, v2
	v_mov_b32_e32 v2, 0x660
	v_mad_u32_u24 v30, v28, s14, v2
	v_mov_b32_e32 v2, 0x770
	v_lshl_add_u64 v[24:25], v[18:19], 0, v[0:1]
	s_barrier
	v_mad_u32_u24 v29, v28, s14, v2
	global_load_dwordx4 v[2:5], v[14:15], off offset:48
	global_load_dwordx4 v[6:9], v[14:15], off offset:32
	global_load_dwordx4 v[10:13], v[14:15], off offset:16
	s_nop 0
	global_load_dwordx4 v[14:17], v[14:15], off
	v_mul_f32_e32 v52, 0xbd020aec, v39
	global_load_dwordx4 v[18:21], v[24:25], off offset:3360
	global_load_dwordx4 v[108:111], v[24:25], off offset:3424
	global_load_dwordx4 v[112:115], v[24:25], off offset:3488
	global_load_dwordx4 v[116:119], v[24:25], off offset:3552
	global_load_dwordx4 v[120:123], v[24:25], off offset:3616
	global_load_dwordx4 v[124:127], v[24:25], off offset:3680
	global_load_dwordx4 v[128:131], v[24:25], off offset:3744
	global_load_dwordx4 v[132:135], v[24:25], off offset:3808
	global_load_dwordx4 v[136:139], v[26:27], off offset:3872
	global_load_dwordx4 v[140:143], v[26:27], off offset:3888
	global_load_dwordx4 v[144:147], v[26:27], off offset:4000
	global_load_dwordx4 v[148:151], v[26:27], off offset:4016
	global_load_dwordx4 v[152:155], v[22:23], off offset:256
	global_load_dwordx4 v[156:159], v[22:23], off offset:272
	global_load_dwordx4 v[160:163], v[22:23], off offset:384
	global_load_dwordx4 v[164:167], v[22:23], off offset:400
	v_mul_f32_e32 v52, 0x3fb8aa3b, v52
	v_exp_f32_e32 v52, v52
	s_movk_i32 s13, 0x880
	v_mul_u32_u24_e32 v36, 0x1100, v28
	v_mul_u32_u24_e32 v38, 0x880, v28
	v_mul_f32_e32 v52, 0x3e000000, v52
	s_waitcnt vmcnt(0)
	v_lshlrev_b32_e32 v0, 16, v18
	v_and_b32_e32 v41, 0xffff0000, v18
	v_lshlrev_b32_e32 v42, 16, v19
	v_and_b32_e32 v43, 0xffff0000, v19
	v_lshlrev_b32_e32 v44, 16, v20
	v_and_b32_e32 v45, 0xffff0000, v20
	v_lshlrev_b32_e32 v46, 16, v21
	v_and_b32_e32 v47, 0xffff0000, v21
	global_load_dwordx4 v[18:21], v[24:25], off offset:3424
	s_waitcnt vmcnt(0)
	v_lshlrev_b32_e32 v48, 16, v18
	v_and_b32_e32 v18, 0xffff0000, v18
	v_mul_f32_e32 v53, v15, v48
	v_mul_f32_e32 v48, v14, v48
	v_fma_f32 v53, v14, v0, -v53
	v_fmac_f32_e32 v48, v15, v0
	v_mul_f32_e32 v0, v17, v18
	v_fma_f32 v0, v16, v41, -v0
	v_mul_f32_e32 v54, v52, v0
	v_mul_f32_e32 v0, v16, v18
	v_lshlrev_b32_e32 v49, 16, v19
	v_fmac_f32_e32 v0, v17, v41
	v_mul_f32_e32 v18, v52, v0
	v_mul_f32_e32 v0, v11, v49
	v_fma_f32 v0, v10, v42, -v0
	v_mul_f32_e32 v41, v52, v0
	v_mul_f32_e32 v0, v10, v49
	v_and_b32_e32 v19, 0xffff0000, v19
	v_fmac_f32_e32 v0, v11, v42
	v_mul_f32_e32 v42, v52, v0
	v_mul_f32_e32 v0, v13, v19
	v_fma_f32 v0, v12, v43, -v0
	v_mul_f32_e32 v49, v52, v0
	v_mul_f32_e32 v0, v12, v19
	v_lshlrev_b32_e32 v50, 16, v20
	v_fmac_f32_e32 v0, v13, v43
	v_mul_f32_e32 v19, v52, v0
	v_mul_f32_e32 v0, v7, v50
	v_fma_f32 v0, v6, v44, -v0
	v_mul_f32_e32 v43, v52, v0
	v_mul_f32_e32 v0, v6, v50
	v_and_b32_e32 v20, 0xffff0000, v20
	v_fmac_f32_e32 v0, v7, v44
	v_mul_f32_e32 v44, v52, v0
	v_mul_f32_e32 v0, v9, v20
	v_fma_f32 v0, v8, v45, -v0
	v_mul_f32_e32 v50, v52, v0
	v_mul_f32_e32 v0, v8, v20
	v_lshlrev_b32_e32 v51, 16, v21
	v_fmac_f32_e32 v0, v9, v45
	v_mul_f32_e32 v20, v52, v0
	v_mul_f32_e32 v0, v3, v51
	v_fma_f32 v0, v2, v46, -v0
	v_mul_f32_e32 v45, v52, v0
	v_mul_f32_e32 v0, v2, v51
	v_and_b32_e32 v21, 0xffff0000, v21
	v_fmac_f32_e32 v0, v3, v46
	v_mul_f32_e32 v46, v52, v0
	v_mul_f32_e32 v0, v5, v21
	v_fma_f32 v0, v4, v47, -v0
	v_mul_f32_e32 v51, v52, v0
	v_mul_f32_e32 v0, v4, v21
	v_fmac_f32_e32 v0, v5, v47
	v_mul_f32_e32 v21, v52, v0
	v_lshlrev_b32_e32 v0, 1, v40
	v_mul_f32_e32 v53, v52, v53
	v_mul_f32_e32 v48, v52, v48
	v_add_u32_e32 v52, 0, v0
	v_mad_u32_u24 v40, v28, s13, v52
	v_cvt_pk_bf16_f32 v18, v18, s0
	ds_write_b16 v40, v18 offset:26384
	v_cvt_pk_bf16_f32 v18, v41, s0
	ds_write_b16 v40, v18 offset:17952
	v_cvt_pk_bf16_f32 v18, v42, s0
	ds_write_b16 v40, v18 offset:26656
	v_cvt_pk_bf16_f32 v18, v49, s0
	ds_write_b16 v40, v18 offset:18224
	v_cvt_pk_bf16_f32 v18, v19, s0
	ds_write_b16 v40, v18 offset:26928
	v_cvt_pk_bf16_f32 v18, v43, s0
	ds_write_b16 v40, v18 offset:18496
	v_cvt_pk_bf16_f32 v18, v44, s0
	ds_write_b16 v40, v18 offset:27200
	v_cvt_pk_bf16_f32 v18, v50, s0
	ds_write_b16 v40, v18 offset:18768
	v_cvt_pk_bf16_f32 v18, v20, s0
	ds_write_b16 v40, v18 offset:27472
	v_cvt_pk_bf16_f32 v18, v45, s0
	v_cvt_pk_bf16_f32 v47, v53, s0
	ds_write_b16 v40, v18 offset:19040
	v_cvt_pk_bf16_f32 v18, v46, s0
	ds_write_b16 v40, v47 offset:17408
	v_cvt_pk_bf16_f32 v47, v48, s0
	ds_write_b16 v40, v18 offset:27744
	v_cvt_pk_bf16_f32 v18, v51, s0
	ds_write_b16 v40, v47 offset:26112
	v_cvt_pk_bf16_f32 v47, v54, s0
	ds_write_b16 v40, v18 offset:19312
	v_cvt_pk_bf16_f32 v18, v21, s0
	ds_write_b16 v40, v47 offset:17680
	ds_write_b16 v40, v18 offset:28016
	global_load_dwordx4 v[18:21], v[26:27], off offset:3888
	global_load_dwordx4 v[40:43], v[26:27], off offset:3872
	v_mul_f32_e32 v54, 0xbc8102b3, v39
	v_mul_f32_e32 v54, 0x3fb8aa3b, v54
	v_exp_f32_e32 v54, v54
	s_movk_i32 s13, 0xf780
	v_mul_f32_e32 v54, 0x3e000000, v54
	s_waitcnt vmcnt(0)
; #define LAS __attribute__((address_space(3)))
; DI unsigned short f2bf(float f) { return (unsigned short)(pk2(f, 0.f) & 0xffffu); }
; DI u32x4 pack8(const float (&v)[8]) { u32x4 w; w.x = pk2(v[0], v[1]); w.y = pk2(v[2], v[3]); w.z = pk2(v[4], v[5]); w.w = pk2(v[6], v[7]); return w; }
; template <int MODE>
; DI void ret_stage(const Args& a, int row0, int h, float lg, LAS bf16_t* Qs, LAS bf16_t* Ks, LAS bf16_t* VT, LAS bf16_t* KT, int tid) {
;     ...
;     { float k1[8], k2[8], o1[8], o2[8]; unpack8(*(const u32x4*)(hr + C_RK + h * 64 + part * 8), k1); unpack8(*(const u32x4*)(hr + C_RK + h * 64 + 32 + part * 8), k2);
;       const float sc = 0.125f * (MODE == 0 ? __expf(lg * (float)(127 - t)) : 1.0f);
; #pragma unroll
;       for (int i = 0; i < 8; ++i) { o1[i] = (k1[i] * cs[2 * i] - k2[i] * cs[2 * i + 1]) * sc; o2[i] = (k1[i] * cs[2 * i + 1] + k2[i] * cs[2 * i]) * sc; }
;       if (MODE == 0) {
; #pragma unroll
;           for (int i = 0; i < 8; ++i) { KT[(part * 8 + i) * PT + t] = f2bf(o1[i]); KT[(32 + part * 8 + i) * PT + t] = f2bf(o2[i]); } }
;       else { *(LAS u32x4*)(Ks + t * PQ + part * 8) = pack8(o1); *(LAS u32x4*)(Ks + t * PQ + 32 + part * 8) = pack8(o2); } }
;     if (MODE == 1) { float q1[8], q2[8], o1[8], o2[8]; unpack8(*(const u32x4*)(hr + C_RQ + h * 64 + part * 8), q1); unpack8(*(const u32x4*)(hr + C_RQ + h * 64 + 32 + part * 8), q2);
; #pragma unroll
;       for (int i = 0; i < 8; ++i) { o1[i] = q1[i] * cs[2 * i] - q2[i] * cs[2 * i + 1]; o2[i] = q1[i] * cs[2 * i + 1] + q2[i] * cs[2 * i]; }
;       *(LAS u32x4*)(Qs + t * PQ + part * 8) = pack8(o1); *(LAS u32x4*)(Qs + t * PQ + 32 + part * 8) = pack8(o2); }
;     { float v[8]; unpack8(*(const u32x4*)(hr + C_RV + h * 64 + part * 16), v);
; #pragma unroll
;       for (int i = 0; i < 8; ++i) VT[(part * 16 + i) * PT + t] = f2bf(v[i]);
;       unpack8(*(const u32x4*)(hr + C_RV + h * 64 + part * 16 + 8), v);
; #pragma unroll
;       for (int i = 0; i < 8; ++i) VT[(part * 16 + 8 + i) * PT + t] = f2bf(v[i]); }
	v_lshlrev_b32_e32 v46, 16, v41
	v_and_b32_e32 v41, 0xffff0000, v41
	v_lshlrev_b32_e32 v44, 16, v40
	v_and_b32_e32 v45, 0xffff0000, v40
	v_lshlrev_b32_e32 v47, 16, v42
	v_mad_u32_u24 v40, v28, s14, v52
	v_cvt_pk_bf16_f32 v41, v41, s0
	v_and_b32_e32 v42, 0xffff0000, v42
	ds_write_b16 v40, v41 offset:816
	v_cvt_pk_bf16_f32 v41, v47, s0
	v_lshlrev_b32_e32 v48, 16, v43
	ds_write_b16 v40, v41 offset:1088
	v_cvt_pk_bf16_f32 v41, v42, s0
	v_and_b32_e32 v43, 0xffff0000, v43
	ds_write_b16 v40, v41 offset:1360
	v_cvt_pk_bf16_f32 v41, v48, s0
	ds_write_b16 v40, v41 offset:1632
	v_cvt_pk_bf16_f32 v41, v43, s0
	v_cvt_pk_bf16_f32 v44, v44, s0
	ds_write_b16 v40, v41 offset:1904
	v_lshlrev_b32_e32 v41, 16, v18
	v_and_b32_e32 v18, 0xffff0000, v18
	ds_write_b16 v40, v44
	v_cvt_pk_bf16_f32 v44, v45, s0
	v_lshlrev_b32_e32 v42, 16, v19
	v_cvt_pk_bf16_f32 v45, v41, s0
	v_add3_u32 v41, 0, v36, v0
	v_cvt_pk_bf16_f32 v18, v18, s0
	v_and_b32_e32 v19, 0xffff0000, v19
	ds_write_b16 v41, v18 offset:2448
	v_cvt_pk_bf16_f32 v18, v42, s0
	v_lshlrev_b32_e32 v43, 16, v20
	ds_write_b16 v41, v18 offset:2720
	v_cvt_pk_bf16_f32 v18, v19, s0
	ds_write_b16 v40, v44 offset:272
	v_cvt_pk_bf16_f32 v44, v46, s0
	v_and_b32_e32 v20, 0xffff0000, v20
	ds_write_b16 v41, v18 offset:2992
	v_cvt_pk_bf16_f32 v18, v43, s0
	ds_write_b16 v40, v44 offset:544
	v_lshlrev_b32_e32 v44, 16, v21
	ds_write_b16 v41, v18 offset:3264
	v_cvt_pk_bf16_f32 v18, v20, s0
	v_and_b32_e32 v21, 0xffff0000, v21
	ds_write_b16 v41, v18 offset:3536
	v_cvt_pk_bf16_f32 v18, v44, s0
	ds_write_b16 v41, v18 offset:3808
	v_cvt_pk_bf16_f32 v18, v21, s0
	ds_write_b16 v41, v18 offset:4080
	global_load_dwordx4 v[18:21], v[24:25], off offset:3488
	ds_write_b16 v41, v45 offset:2176
	s_waitcnt vmcnt(0)
	v_lshlrev_b32_e32 v42, 16, v18
	v_and_b32_e32 v43, 0xffff0000, v18
	v_lshlrev_b32_e32 v44, 16, v19
	v_and_b32_e32 v45, 0xffff0000, v19
	v_lshlrev_b32_e32 v46, 16, v20
	v_and_b32_e32 v47, 0xffff0000, v20
	v_lshlrev_b32_e32 v48, 16, v21
	v_and_b32_e32 v49, 0xffff0000, v21
	global_load_dwordx4 v[18:21], v[24:25], off offset:3552
	s_waitcnt vmcnt(0)
	v_lshlrev_b32_e32 v50, 16, v18
	v_mul_f32_e32 v55, v15, v50
	v_mul_f32_e32 v50, v14, v50
	v_and_b32_e32 v18, 0xffff0000, v18
	v_fmac_f32_e32 v50, v15, v42
	v_lshlrev_b32_e32 v51, 16, v19
	v_fma_f32 v55, v14, v42, -v55
	v_mul_f32_e32 v42, v54, v50
	v_mul_f32_e32 v50, v17, v18
	v_mul_f32_e32 v18, v16, v18
	v_fma_f32 v50, v16, v43, -v50
	v_fmac_f32_e32 v18, v17, v43
	v_mul_f32_e32 v43, v11, v51
	v_mul_f32_e32 v51, v10, v51
	v_and_b32_e32 v19, 0xffff0000, v19
	v_fmac_f32_e32 v51, v11, v44
	v_lshlrev_b32_e32 v52, 16, v20
	v_fma_f32 v43, v10, v44, -v43
	v_mul_f32_e32 v44, v54, v51
	v_mul_f32_e32 v51, v13, v19
	v_mul_f32_e32 v19, v12, v19
	v_fma_f32 v51, v12, v45, -v51
	v_fmac_f32_e32 v19, v13, v45
	v_mul_f32_e32 v45, v7, v52
	v_mul_f32_e32 v52, v6, v52
	v_and_b32_e32 v20, 0xffff0000, v20
	v_fmac_f32_e32 v52, v7, v46
	v_lshlrev_b32_e32 v53, 16, v21
	v_fma_f32 v45, v6, v46, -v45
	v_mul_f32_e32 v46, v54, v52
	v_mul_f32_e32 v52, v9, v20
	v_mul_f32_e32 v20, v8, v20
	v_fma_f32 v52, v8, v47, -v52
	v_fmac_f32_e32 v20, v9, v47
	v_mul_f32_e32 v47, v3, v53
	v_mul_f32_e32 v53, v2, v53
	v_and_b32_e32 v21, 0xffff0000, v21
	v_fmac_f32_e32 v53, v3, v48
	v_fma_f32 v47, v2, v48, -v47
	v_mul_f32_e32 v48, v54, v53
	v_mul_f32_e32 v53, v5, v21
	v_mul_f32_e32 v21, v4, v21
	v_mul_f32_e32 v18, v54, v18
	v_fma_f32 v53, v4, v49, -v53
	v_fmac_f32_e32 v21, v5, v49
	v_mul_f32_e32 v55, v54, v55
	v_mul_f32_e32 v50, v54, v50
	v_mul_f32_e32 v43, v54, v43
	v_mul_f32_e32 v51, v54, v51
	v_mul_f32_e32 v19, v54, v19
	v_mul_f32_e32 v45, v54, v45
	v_mul_f32_e32 v52, v54, v52
	v_mul_f32_e32 v20, v54, v20
	v_mul_f32_e32 v47, v54, v47
	v_mul_f32_e32 v53, v54, v53
	v_mul_f32_e32 v21, v54, v21
	v_mad_i32_i24 v54, v28, s13, v41
	v_cvt_pk_bf16_f32 v18, v18, s0
	ds_write_b16 v54, v18 offset:61200
	v_cvt_pk_bf16_f32 v18, v43, s0
	ds_write_b16 v54, v18 offset:52768
	v_cvt_pk_bf16_f32 v18, v44, s0
	ds_write_b16 v54, v18 offset:61472
	v_cvt_pk_bf16_f32 v18, v51, s0
	ds_write_b16 v54, v18 offset:53040
	v_cvt_pk_bf16_f32 v18, v19, s0
	ds_write_b16 v54, v18 offset:61744
	v_cvt_pk_bf16_f32 v18, v45, s0
	ds_write_b16 v54, v18 offset:53312
	v_cvt_pk_bf16_f32 v18, v46, s0
	ds_write_b16 v54, v18 offset:62016
	v_cvt_pk_bf16_f32 v18, v52, s0
	ds_write_b16 v54, v18 offset:53584
	v_cvt_pk_bf16_f32 v18, v20, s0
	ds_write_b16 v54, v18 offset:62288
	v_cvt_pk_bf16_f32 v18, v47, s0
	ds_write_b16 v54, v18 offset:53856
	v_cvt_pk_bf16_f32 v18, v48, s0
	v_cvt_pk_bf16_f32 v42, v42, s0
	ds_write_b16 v54, v18 offset:62560
	v_cvt_pk_bf16_f32 v18, v53, s0
	v_cvt_pk_bf16_f32 v49, v55, s0
	ds_write_b16 v54, v42 offset:60928
	v_cvt_pk_bf16_f32 v42, v50, s0
	ds_write_b16 v54, v18 offset:54128
	v_cvt_pk_bf16_f32 v18, v21, s0
	ds_write_b16 v54, v49 offset:52224
	ds_write_b16 v54, v42 offset:52496
	ds_write_b16 v54, v18 offset:62832
	global_load_dwordx4 v[18:21], v[26:27], off offset:4016
	global_load_dwordx4 v[42:45], v[26:27], off offset:4000
	v_mul_f32_e32 v50, 0xbc0080ac, v39
	v_mul_f32_e32 v50, 0x3fb8aa3b, v50
	v_exp_f32_e32 v50, v50
	v_readlane_b32 s13, v254, 45
	v_mul_f32_e32 v39, 0xbb80402b, v39
	v_mul_f32_e32 v39, 0x3fb8aa3b, v39
	v_mul_f32_e32 v50, 0x3e000000, v50
	v_exp_f32_e32 v39, v39
	s_waitcnt vmcnt(0)
; #define LAS __attribute__((address_space(3)))
; DI unsigned short f2bf(float f) { return (unsigned short)(pk2(f, 0.f) & 0xffffu); }
; DI u32x4 pack8(const float (&v)[8]) { u32x4 w; w.x = pk2(v[0], v[1]); w.y = pk2(v[2], v[3]); w.z = pk2(v[4], v[5]); w.w = pk2(v[6], v[7]); return w; }
; template <int MODE>
; DI void ret_stage(const Args& a, int row0, int h, float lg, LAS bf16_t* Qs, LAS bf16_t* Ks, LAS bf16_t* VT, LAS bf16_t* KT, int tid) {
;     ...
;     { float k1[8], k2[8], o1[8], o2[8]; unpack8(*(const u32x4*)(hr + C_RK + h * 64 + part * 8), k1); unpack8(*(const u32x4*)(hr + C_RK + h * 64 + 32 + part * 8), k2);
;       const float sc = 0.125f * (MODE == 0 ? __expf(lg * (float)(127 - t)) : 1.0f);
; #pragma unroll
;       for (int i = 0; i < 8; ++i) { o1[i] = (k1[i] * cs[2 * i] - k2[i] * cs[2 * i + 1]) * sc; o2[i] = (k1[i] * cs[2 * i + 1] + k2[i] * cs[2 * i]) * sc; }
;       if (MODE == 0) {
; #pragma unroll
;           for (int i = 0; i < 8; ++i) { KT[(part * 8 + i) * PT + t] = f2bf(o1[i]); KT[(32 + part * 8 + i) * PT + t] = f2bf(o2[i]); } }
;       else { *(LAS u32x4*)(Ks + t * PQ + part * 8) = pack8(o1); *(LAS u32x4*)(Ks + t * PQ + 32 + part * 8) = pack8(o2); } }
;     if (MODE == 1) { float q1[8], q2[8], o1[8], o2[8]; unpack8(*(const u32x4*)(hr + C_RQ + h * 64 + part * 8), q1); unpack8(*(const u32x4*)(hr + C_RQ + h * 64 + 32 + part * 8), q2);
; #pragma unroll
;       for (int i = 0; i < 8; ++i) { o1[i] = q1[i] * cs[2 * i] - q2[i] * cs[2 * i + 1]; o2[i] = q1[i] * cs[2 * i + 1] + q2[i] * cs[2 * i]; }
;       *(LAS u32x4*)(Qs + t * PQ + part * 8) = pack8(o1); *(LAS u32x4*)(Qs + t * PQ + 32 + part * 8) = pack8(o2); }
;     { float v[8]; unpack8(*(const u32x4*)(hr + C_RV + h * 64 + part * 16), v);
; #pragma unroll
;       for (int i = 0; i < 8; ++i) VT[(part * 16 + i) * PT + t] = f2bf(v[i]);
;       unpack8(*(const u32x4*)(hr + C_RV + h * 64 + part * 16 + 8), v);
; #pragma unroll
;       for (int i = 0; i < 8; ++i) VT[(part * 16 + 8 + i) * PT + t] = f2bf(v[i]); }
	v_lshlrev_b32_e32 v26, 16, v42
	v_and_b32_e32 v27, 0xffff0000, v42
	v_cvt_pk_bf16_f32 v26, v26, s0
	v_lshlrev_b32_e32 v42, 16, v43
	ds_write_b16 v40, v26 offset:34816
	v_cvt_pk_bf16_f32 v26, v27, s0
	v_and_b32_e32 v43, 0xffff0000, v43
	ds_write_b16 v40, v26 offset:35088
	v_cvt_pk_bf16_f32 v26, v42, s0
	v_lshlrev_b32_e32 v46, 16, v44
	ds_write_b16 v40, v26 offset:35360
	v_cvt_pk_bf16_f32 v26, v43, s0
	v_and_b32_e32 v44, 0xffff0000, v44
	ds_write_b16 v40, v26 offset:35632
	v_cvt_pk_bf16_f32 v26, v46, s0
	v_lshlrev_b32_e32 v47, 16, v45
	ds_write_b16 v40, v26 offset:35904
	v_cvt_pk_bf16_f32 v26, v44, s0
	v_and_b32_e32 v45, 0xffff0000, v45
	ds_write_b16 v40, v26 offset:36176
	v_cvt_pk_bf16_f32 v26, v47, s0
	ds_write_b16 v40, v26 offset:36448
	v_cvt_pk_bf16_f32 v26, v45, s0
	ds_write_b16 v40, v26 offset:36720
	v_lshlrev_b32_e32 v26, 16, v18
	v_and_b32_e32 v18, 0xffff0000, v18
	v_lshlrev_b32_e32 v27, 16, v19
	v_cvt_pk_bf16_f32 v18, v18, s0
	v_and_b32_e32 v19, 0xffff0000, v19
	ds_write_b16 v41, v18 offset:37264
	v_cvt_pk_bf16_f32 v18, v27, s0
	v_lshlrev_b32_e32 v40, 16, v20
	ds_write_b16 v41, v18 offset:37536
	v_cvt_pk_bf16_f32 v18, v19, s0
	v_and_b32_e32 v20, 0xffff0000, v20
	ds_write_b16 v41, v18 offset:37808
	v_cvt_pk_bf16_f32 v18, v40, s0
	v_lshlrev_b32_e32 v42, 16, v21
	ds_write_b16 v41, v18 offset:38080
	v_cvt_pk_bf16_f32 v18, v20, s0
	v_and_b32_e32 v21, 0xffff0000, v21
	ds_write_b16 v41, v18 offset:38352
	v_cvt_pk_bf16_f32 v18, v42, s0
	ds_write_b16 v41, v18 offset:38624
	v_cvt_pk_bf16_f32 v18, v21, s0
	ds_write_b16 v41, v18 offset:38896
	global_load_dwordx4 v[18:21], v[24:25], off offset:3616
	v_cvt_pk_bf16_f32 v26, v26, s0
	ds_write_b16 v41, v26 offset:36992
	v_mul_f32_e32 v39, 0x3e000000, v39
	s_waitcnt vmcnt(0)
	v_lshlrev_b32_e32 v26, 16, v18
	v_and_b32_e32 v27, 0xffff0000, v18
	v_lshlrev_b32_e32 v40, 16, v19
	v_and_b32_e32 v41, 0xffff0000, v19
	v_lshlrev_b32_e32 v42, 16, v20
	v_and_b32_e32 v43, 0xffff0000, v20
	v_lshlrev_b32_e32 v44, 16, v21
	v_and_b32_e32 v45, 0xffff0000, v21
	global_load_dwordx4 v[18:21], v[24:25], off offset:3680
	s_waitcnt vmcnt(0)
	v_lshlrev_b32_e32 v46, 16, v18
	v_mul_f32_e32 v51, v15, v46
	v_mul_f32_e32 v46, v14, v46
	v_and_b32_e32 v18, 0xffff0000, v18
	v_fmac_f32_e32 v46, v15, v26
	v_lshlrev_b32_e32 v47, 16, v19
	v_fma_f32 v51, v14, v26, -v51
	v_mul_f32_e32 v26, v50, v46
	v_mul_f32_e32 v46, v17, v18
	v_mul_f32_e32 v18, v16, v18
	v_fma_f32 v46, v16, v27, -v46
	v_fmac_f32_e32 v18, v17, v27
	v_mul_f32_e32 v27, v11, v47
	v_mul_f32_e32 v47, v10, v47
	v_and_b32_e32 v19, 0xffff0000, v19
	v_fmac_f32_e32 v47, v11, v40
	v_lshlrev_b32_e32 v48, 16, v20
	v_fma_f32 v27, v10, v40, -v27
	v_mul_f32_e32 v40, v50, v47
	v_mul_f32_e32 v47, v13, v19
	v_mul_f32_e32 v19, v12, v19
	v_fma_f32 v47, v12, v41, -v47
	v_fmac_f32_e32 v19, v13, v41
	v_mul_f32_e32 v41, v7, v48
	v_mul_f32_e32 v48, v6, v48
	v_and_b32_e32 v20, 0xffff0000, v20
	v_fmac_f32_e32 v48, v7, v42
	v_lshlrev_b32_e32 v49, 16, v21
	v_fma_f32 v41, v6, v42, -v41
	v_mul_f32_e32 v42, v50, v48
	v_mul_f32_e32 v48, v9, v20
	v_mul_f32_e32 v20, v8, v20
	v_fma_f32 v48, v8, v43, -v48
	v_fmac_f32_e32 v20, v9, v43
	v_mul_f32_e32 v43, v3, v49
	v_mul_f32_e32 v49, v2, v49
	v_and_b32_e32 v21, 0xffff0000, v21
	v_fmac_f32_e32 v49, v3, v44
	v_fma_f32 v43, v2, v44, -v43
	v_mul_f32_e32 v44, v50, v49
	v_mul_f32_e32 v49, v5, v21
	v_mul_f32_e32 v21, v4, v21
	v_mul_f32_e32 v18, v50, v18
	v_fma_f32 v49, v4, v45, -v49
	v_fmac_f32_e32 v21, v5, v45
	v_mul_f32_e32 v51, v50, v51
	v_mul_f32_e32 v46, v50, v46
	v_mul_f32_e32 v27, v50, v27
	v_mul_f32_e32 v47, v50, v47
	v_mul_f32_e32 v19, v50, v19
	v_mul_f32_e32 v41, v50, v41
	v_mul_f32_e32 v48, v50, v48
	v_mul_f32_e32 v20, v50, v20
	v_mul_f32_e32 v43, v50, v43
	v_mul_f32_e32 v49, v50, v49
	v_mul_f32_e32 v21, v50, v21
	v_add3_u32 v50, s13, v38, v0
	v_cvt_pk_bf16_f32 v18, v18, s0
	ds_write_b16 v50, v18 offset:8976
	v_cvt_pk_bf16_f32 v18, v27, s0
	ds_write_b16 v50, v18 offset:544
	v_cvt_pk_bf16_f32 v18, v40, s0
	ds_write_b16 v50, v18 offset:9248
	v_cvt_pk_bf16_f32 v18, v47, s0
	ds_write_b16 v50, v18 offset:816
	v_cvt_pk_bf16_f32 v18, v19, s0
	ds_write_b16 v50, v18 offset:9520
	v_cvt_pk_bf16_f32 v18, v41, s0
	ds_write_b16 v50, v18 offset:1088
	v_cvt_pk_bf16_f32 v18, v42, s0
	ds_write_b16 v50, v18 offset:9792
	v_cvt_pk_bf16_f32 v18, v48, s0
	ds_write_b16 v50, v18 offset:1360
	v_cvt_pk_bf16_f32 v18, v20, s0
	ds_write_b16 v50, v18 offset:10064
	v_cvt_pk_bf16_f32 v18, v43, s0
	ds_write_b16 v50, v18 offset:1632
	v_cvt_pk_bf16_f32 v18, v44, s0
	v_cvt_pk_bf16_f32 v26, v26, s0
	ds_write_b16 v50, v18 offset:10336
	v_cvt_pk_bf16_f32 v18, v49, s0
	v_cvt_pk_bf16_f32 v45, v51, s0
	ds_write_b16 v50, v26 offset:8704
	v_cvt_pk_bf16_f32 v26, v46, s0
	ds_write_b16 v50, v18 offset:1904
	v_cvt_pk_bf16_f32 v18, v21, s0
	ds_write_b16 v50, v45
	ds_write_b16 v50, v26 offset:272
	ds_write_b16 v50, v18 offset:10608
	global_load_dwordx4 v[18:21], v[22:23], off offset:272
	global_load_dwordx4 v[40:43], v[22:23], off offset:256
	s_add_i32 s13, 0, 0x11000
	v_add_u32_e32 v46, s13, v0
	v_mad_u32_u24 v47, v28, s14, v46
	s_waitcnt vmcnt(0)
; #define LAS __attribute__((address_space(3)))
; DI unsigned short f2bf(float f) { return (unsigned short)(pk2(f, 0.f) & 0xffffu); }
; DI u32x4 pack8(const float (&v)[8]) { u32x4 w; w.x = pk2(v[0], v[1]); w.y = pk2(v[2], v[3]); w.z = pk2(v[4], v[5]); w.w = pk2(v[6], v[7]); return w; }
; template <int MODE>
; DI void ret_stage(const Args& a, int row0, int h, float lg, LAS bf16_t* Qs, LAS bf16_t* Ks, LAS bf16_t* VT, LAS bf16_t* KT, int tid) {
;     ...
;     { float k1[8], k2[8], o1[8], o2[8]; unpack8(*(const u32x4*)(hr + C_RK + h * 64 + part * 8), k1); unpack8(*(const u32x4*)(hr + C_RK + h * 64 + 32 + part * 8), k2);
;       const float sc = 0.125f * (MODE == 0 ? __expf(lg * (float)(127 - t)) : 1.0f);
; #pragma unroll
;       for (int i = 0; i < 8; ++i) { o1[i] = (k1[i] * cs[2 * i] - k2[i] * cs[2 * i + 1]) * sc; o2[i] = (k1[i] * cs[2 * i + 1] + k2[i] * cs[2 * i]) * sc; }
;       if (MODE == 0) {
; #pragma unroll
;           for (int i = 0; i < 8; ++i) { KT[(part * 8 + i) * PT + t] = f2bf(o1[i]); KT[(32 + part * 8 + i) * PT + t] = f2bf(o2[i]); } }
;       else { *(LAS u32x4*)(Ks + t * PQ + part * 8) = pack8(o1); *(LAS u32x4*)(Ks + t * PQ + 32 + part * 8) = pack8(o2); } }
;     if (MODE == 1) { float q1[8], q2[8], o1[8], o2[8]; unpack8(*(const u32x4*)(hr + C_RQ + h * 64 + part * 8), q1); unpack8(*(const u32x4*)(hr + C_RQ + h * 64 + 32 + part * 8), q2);
; #pragma unroll
;       for (int i = 0; i < 8; ++i) { o1[i] = q1[i] * cs[2 * i] - q2[i] * cs[2 * i + 1]; o2[i] = q1[i] * cs[2 * i + 1] + q2[i] * cs[2 * i]; }
;       *(LAS u32x4*)(Qs + t * PQ + part * 8) = pack8(o1); *(LAS u32x4*)(Qs + t * PQ + 32 + part * 8) = pack8(o2); }
;     { float v[8]; unpack8(*(const u32x4*)(hr + C_RV + h * 64 + part * 16), v);
; #pragma unroll
;       for (int i = 0; i < 8; ++i) VT[(part * 16 + i) * PT + t] = f2bf(v[i]);
;       unpack8(*(const u32x4*)(hr + C_RV + h * 64 + part * 16 + 8), v);
; #pragma unroll
;       for (int i = 0; i < 8; ++i) VT[(part * 16 + 8 + i) * PT + t] = f2bf(v[i]); }
	v_lshlrev_b32_e32 v26, 16, v40
	v_and_b32_e32 v27, 0xffff0000, v40
	v_cvt_pk_bf16_f32 v26, v26, s0
	v_lshlrev_b32_e32 v40, 16, v41
	ds_write_b16 v47, v26
	v_cvt_pk_bf16_f32 v26, v27, s0
	v_and_b32_e32 v41, 0xffff0000, v41
	ds_write_b16 v47, v26 offset:272
	v_cvt_pk_bf16_f32 v26, v40, s0
	v_lshlrev_b32_e32 v44, 16, v42
	ds_write_b16 v47, v26 offset:544
	v_cvt_pk_bf16_f32 v26, v41, s0
	v_and_b32_e32 v42, 0xffff0000, v42
	ds_write_b16 v47, v26 offset:816
	v_cvt_pk_bf16_f32 v26, v44, s0
	v_lshlrev_b32_e32 v45, 16, v43
	ds_write_b16 v47, v26 offset:1088
	v_cvt_pk_bf16_f32 v26, v42, s0
	v_and_b32_e32 v43, 0xffff0000, v43
	ds_write_b16 v47, v26 offset:1360
	v_cvt_pk_bf16_f32 v26, v45, s0
	ds_write_b16 v47, v26 offset:1632
	v_cvt_pk_bf16_f32 v26, v43, s0
	ds_write_b16 v47, v26 offset:1904
	v_lshlrev_b32_e32 v26, 16, v18
	v_and_b32_e32 v18, 0xffff0000, v18
	v_cvt_pk_bf16_f32 v26, v26, s0
	v_add3_u32 v42, s13, v36, v0
	v_lshlrev_b32_e32 v27, 16, v19
	ds_write_b16 v42, v26 offset:2176
	v_cvt_pk_bf16_f32 v18, v18, s0
	v_add_u32_e32 v26, v46, v37
	v_and_b32_e32 v19, 0xffff0000, v19
	ds_write_b16 v26, v18 offset:2176
	v_cvt_pk_bf16_f32 v18, v27, s0
	v_add_u32_e32 v26, v46, v35
	v_lshlrev_b32_e32 v40, 16, v20
	ds_write_b16 v26, v18 offset:2176
	v_cvt_pk_bf16_f32 v18, v19, s0
	v_add_u32_e32 v19, v46, v33
	v_and_b32_e32 v20, 0xffff0000, v20
	ds_write_b16 v19, v18 offset:2176
	v_cvt_pk_bf16_f32 v18, v40, s0
	v_add_u32_e32 v19, v46, v32
	v_lshlrev_b32_e32 v41, 16, v21
	ds_write_b16 v19, v18 offset:2176
	v_cvt_pk_bf16_f32 v18, v20, s0
	v_add_u32_e32 v19, v46, v31
	v_and_b32_e32 v21, 0xffff0000, v21
	ds_write_b16 v19, v18 offset:2176
	v_cvt_pk_bf16_f32 v18, v41, s0
	v_add_u32_e32 v19, v46, v30
	ds_write_b16 v19, v18 offset:2176
	v_cvt_pk_bf16_f32 v18, v21, s0
	v_add_u32_e32 v19, v46, v29
	ds_write_b16 v19, v18 offset:2176
	global_load_dwordx4 v[18:21], v[24:25], off offset:3744
	v_readlane_b32 s13, v254, 46
	s_waitcnt vmcnt(0)
	v_lshlrev_b32_e32 v26, 16, v18
	v_and_b32_e32 v27, 0xffff0000, v18
	v_lshlrev_b32_e32 v40, 16, v19
	v_and_b32_e32 v41, 0xffff0000, v19
	v_lshlrev_b32_e32 v42, 16, v20
	v_and_b32_e32 v43, 0xffff0000, v20
	v_lshlrev_b32_e32 v44, 16, v21
	v_and_b32_e32 v45, 0xffff0000, v21
	global_load_dwordx4 v[18:21], v[24:25], off offset:3808
	s_waitcnt vmcnt(0)
	v_lshlrev_b32_e32 v24, 16, v18
	v_mul_f32_e32 v48, v15, v24
	v_and_b32_e32 v18, 0xffff0000, v18
	v_fma_f32 v48, v14, v26, -v48
	v_mul_f32_e32 v14, v14, v24
	v_fmac_f32_e32 v14, v15, v26
	v_mul_f32_e32 v15, v17, v18
	v_lshlrev_b32_e32 v25, 16, v19
	v_fma_f32 v15, v16, v27, -v15
	v_mul_f32_e32 v16, v16, v18
	v_fmac_f32_e32 v16, v17, v27
	v_mul_f32_e32 v17, v11, v25
	v_and_b32_e32 v19, 0xffff0000, v19
	v_fma_f32 v17, v10, v40, -v17
	v_mul_f32_e32 v10, v10, v25
	v_fmac_f32_e32 v10, v11, v40
	v_mul_f32_e32 v11, v13, v19
	v_lshlrev_b32_e32 v46, 16, v20
	v_fma_f32 v11, v12, v41, -v11
	v_mul_f32_e32 v12, v12, v19
	v_fmac_f32_e32 v12, v13, v41
	v_mul_f32_e32 v13, v7, v46
	v_and_b32_e32 v20, 0xffff0000, v20
	v_fma_f32 v13, v6, v42, -v13
	v_mul_f32_e32 v6, v6, v46
	v_fmac_f32_e32 v6, v7, v42
	v_mul_f32_e32 v7, v9, v20
	v_lshlrev_b32_e32 v47, 16, v21
	v_fma_f32 v7, v8, v43, -v7
	v_mul_f32_e32 v8, v8, v20
	v_fmac_f32_e32 v8, v9, v43
	v_mul_f32_e32 v9, v3, v47
	v_and_b32_e32 v21, 0xffff0000, v21
	v_fma_f32 v9, v2, v44, -v9
	v_mul_f32_e32 v2, v2, v47
	v_fmac_f32_e32 v2, v3, v44
	v_mul_f32_e32 v3, v5, v21
	v_mul_f32_e32 v48, v39, v48
	v_fma_f32 v3, v4, v45, -v3
	v_mul_f32_e32 v4, v4, v21
	v_mul_f32_e32 v14, v39, v14
	v_fmac_f32_e32 v4, v5, v45
	v_cvt_pk_bf16_f32 v5, v48, s0
	v_add3_u32 v18, s13, v38, v0
	v_mul_f32_e32 v15, v39, v15
	ds_write_b16 v18, v5
	v_cvt_pk_bf16_f32 v5, v14, s0
	v_mul_f32_e32 v16, v39, v16
	ds_write_b16 v18, v5 offset:8704
	v_cvt_pk_bf16_f32 v5, v15, s0
	v_mul_f32_e32 v17, v39, v17
	ds_write_b16 v18, v5 offset:272
	v_cvt_pk_bf16_f32 v5, v16, s0
	v_mul_f32_e32 v10, v39, v10
	ds_write_b16 v18, v5 offset:8976
	v_cvt_pk_bf16_f32 v5, v17, s0
	v_mul_f32_e32 v11, v39, v11
	ds_write_b16 v18, v5 offset:544
	v_cvt_pk_bf16_f32 v5, v10, s0
	v_mul_f32_e32 v12, v39, v12
	ds_write_b16 v18, v5 offset:9248
	v_cvt_pk_bf16_f32 v5, v11, s0
	v_mul_f32_e32 v13, v39, v13
	ds_write_b16 v18, v5 offset:816
	v_cvt_pk_bf16_f32 v5, v12, s0
	v_mul_f32_e32 v6, v39, v6
	ds_write_b16 v18, v5 offset:9520
	v_cvt_pk_bf16_f32 v5, v13, s0
	v_mul_f32_e32 v7, v39, v7
	v_mul_f32_e32 v2, v39, v2
	ds_write_b16 v18, v5 offset:1088
	v_cvt_pk_bf16_f32 v5, v6, s0
	v_mul_f32_e32 v8, v39, v8
	v_mul_f32_e32 v3, v39, v3
	ds_write_b16 v18, v5 offset:9792
	v_cvt_pk_bf16_f32 v5, v7, s0
	v_cvt_pk_bf16_f32 v2, v2, s0
	v_mul_f32_e32 v9, v39, v9
	v_mul_f32_e32 v4, v39, v4
	ds_write_b16 v18, v5 offset:1360
	v_cvt_pk_bf16_f32 v5, v8, s0
	ds_write_b16 v18, v2 offset:10336
	v_cvt_pk_bf16_f32 v2, v3, s0
	ds_write_b16 v18, v5 offset:10064
	v_cvt_pk_bf16_f32 v5, v9, s0
	ds_write_b16 v18, v2 offset:1904
	v_cvt_pk_bf16_f32 v2, v4, s0
	ds_write_b16 v18, v5 offset:1632
	ds_write_b16 v18, v2 offset:10608
	global_load_dwordx4 v[2:5], v[22:23], off offset:400
	global_load_dwordx4 v[6:9], v[22:23], off offset:384
	v_readlane_b32 s13, v254, 47
	s_waitcnt vmcnt(0)
; #define LAS __attribute__((address_space(3)))
; DI unsigned short f2bf(float f) { return (unsigned short)(pk2(f, 0.f) & 0xffffu); }
; template <int MODE>
; DI void ret_stage(const Args& a, int row0, int h, float lg, LAS bf16_t* Qs, LAS bf16_t* Ks, LAS bf16_t* VT, LAS bf16_t* KT, int tid) {
;     ...
;     { float v[8]; unpack8(*(const u32x4*)(hr + C_RV + h * 64 + part * 16), v);
; #pragma unroll
;       for (int i = 0; i < 8; ++i) VT[(part * 16 + i) * PT + t] = f2bf(v[i]);
;       unpack8(*(const u32x4*)(hr + C_RV + h * 64 + part * 16 + 8), v);
; #pragma unroll
;       for (int i = 0; i < 8; ++i) VT[(part * 16 + 8 + i) * PT + t] = f2bf(v[i]); }
; DI void ret_pass1(LAS unsigned char* lds, const Args& a, int unit, int wv) {
;     ...
;     __syncthreads();
;     const int h = wave >> 1, e0 = (wave & 1) * 32;
;     LAS bf16_t* VT = (LAS bf16_t*)(lds + h * 34816); LAS bf16_t* KT = (LAS bf16_t*)(lds + h * 34816 + 17408);
;     f32x4 acc[4][2]; zero_acc(acc);
	v_lshlrev_b32_e32 v10, 16, v6
	v_and_b32_e32 v6, 0xffff0000, v6
	v_add_u32_e32 v14, s13, v0
	v_lshlrev_b32_e32 v11, 16, v7
	v_mad_u32_u24 v15, v28, s14, v14
	v_cvt_pk_bf16_f32 v6, v6, s0
	v_and_b32_e32 v7, 0xffff0000, v7
	ds_write_b16 v15, v6 offset:272
	v_cvt_pk_bf16_f32 v6, v11, s0
	v_lshlrev_b32_e32 v12, 16, v8
	ds_write_b16 v15, v6 offset:544
	v_cvt_pk_bf16_f32 v6, v7, s0
	v_and_b32_e32 v8, 0xffff0000, v8
	ds_write_b16 v15, v6 offset:816
	v_cvt_pk_bf16_f32 v6, v12, s0
	v_lshlrev_b32_e32 v13, 16, v9
	ds_write_b16 v15, v6 offset:1088
	v_cvt_pk_bf16_f32 v6, v8, s0
	v_and_b32_e32 v9, 0xffff0000, v9
	ds_write_b16 v15, v6 offset:1360
	v_cvt_pk_bf16_f32 v6, v13, s0
	ds_write_b16 v15, v6 offset:1632
	v_cvt_pk_bf16_f32 v6, v9, s0
	ds_write_b16 v15, v6 offset:1904
	v_lshlrev_b32_e32 v6, 16, v2
	v_and_b32_e32 v2, 0xffff0000, v2
	v_cvt_pk_bf16_f32 v6, v6, s0
	v_add3_u32 v0, s13, v36, v0
	v_lshlrev_b32_e32 v7, 16, v3
	ds_write_b16 v0, v6 offset:2176
	v_cvt_pk_bf16_f32 v0, v2, s0
	v_add_u32_e32 v2, v14, v37
	v_and_b32_e32 v3, 0xffff0000, v3
	ds_write_b16 v2, v0 offset:2176
	v_cvt_pk_bf16_f32 v0, v7, s0
	v_add_u32_e32 v2, v14, v35
	v_lshlrev_b32_e32 v8, 16, v4
	ds_write_b16 v2, v0 offset:2176
	v_cvt_pk_bf16_f32 v0, v3, s0
	v_add_u32_e32 v2, v14, v33
	v_and_b32_e32 v4, 0xffff0000, v4
	ds_write_b16 v2, v0 offset:2176
	v_cvt_pk_bf16_f32 v0, v8, s0
	v_add_u32_e32 v2, v14, v32
	v_lshlrev_b32_e32 v9, 16, v5
	ds_write_b16 v2, v0 offset:2176
	v_cvt_pk_bf16_f32 v0, v4, s0
	v_add_u32_e32 v2, v14, v31
	v_and_b32_e32 v5, 0xffff0000, v5
	ds_write_b16 v2, v0 offset:2176
	v_cvt_pk_bf16_f32 v0, v9, s0
	v_add_u32_e32 v2, v14, v30
	ds_write_b16 v2, v0 offset:2176
	v_cvt_pk_bf16_f32 v0, v5, s0
	v_add_u32_e32 v2, v14, v29
	ds_write_b16 v2, v0 offset:2176
	v_and_b32_e32 v0, 15, v34
	v_mul_u32_u24_e32 v2, 0x110, v0
	v_and_b32_e32 v3, 48, v34
	v_readlane_b32 s13, v254, 8
	v_cvt_pk_bf16_f32 v10, v10, s0
	ds_write_b16 v15, v10
	v_add3_u32 v35, s13, v2, v3
	v_mov_b32_e32 v2, 0
	s_movk_i32 s13, 0xffe0
	v_mov_b32_e32 v3, v2
	v_mov_b32_e32 v4, v2
	v_mov_b32_e32 v5, v2
	v_mov_b32_e32 v6, v2
	v_mov_b32_e32 v7, v2
	v_mov_b32_e32 v8, v2
	v_mov_b32_e32 v9, v2
	v_mov_b32_e32 v10, v2
	v_mov_b32_e32 v11, v2
	v_mov_b32_e32 v12, v2
	v_mov_b32_e32 v13, v2
	v_mov_b32_e32 v14, v2
	v_mov_b32_e32 v15, v2
	v_mov_b32_e32 v16, v2
	v_mov_b32_e32 v17, v2
	v_mov_b32_e32 v18, v2
	v_mov_b32_e32 v19, v2
	v_mov_b32_e32 v20, v2
	v_mov_b32_e32 v21, v2
	v_mov_b32_e32 v22, v2
	v_mov_b32_e32 v23, v2
	v_mov_b32_e32 v24, v2
	v_mov_b32_e32 v25, v2
	v_mov_b32_e32 v26, v2
	v_mov_b32_e32 v27, v2
	v_mov_b32_e32 v28, v2
	v_mov_b32_e32 v29, v2
	v_mov_b32_e32 v30, v2
	v_mov_b32_e32 v31, v2
	v_mov_b32_e32 v32, v2
	v_mov_b32_e32 v33, v2
	s_waitcnt lgkmcnt(0)
	s_barrier

; DI void chunk_scans(const Args& a, int tid) {
;     ...
;     for (int n = gt; n < 2 * DFF; n += NT) { const float* p1 = (const float*)(a.ws + WS_W + W_PART1) + n; const float* p2 = (const float*)(a.ws + WS_W + W_PART2) + n; float s1 = 0.f, s2 = 0.f;
; #pragma unroll
;         for (int kb = 0; kb < 16; ++kb) { s1 += p1[(size_t)kb * 2 * DFF]; s2 += p2[(size_t)kb * 2 * DFF]; }
;         ((float*)(a.ws + WS_W + W_C1F))[n] = s1; ((float*)(a.ws + WS_W + W_C2F))[n] = s2; }
.LBB0_1235:
	global_load_dword v110, v[4:5], off
	s_mov_b32 s12, 0x10000
	v_add_u32_e32 v3, s20, v3
	v_add_co_u32_e32 v6, vcc, 0x60000, v4
	s_nop 1
	v_addc_co_u32_e32 v7, vcc, 0, v5, vcc
	global_load_dword v111, v[6:7], off
	v_add_co_u32_e32 v6, vcc, 0x5000, v4
	s_nop 1
	v_addc_co_u32_e32 v7, vcc, 0, v5, vcc
	global_load_dword v112, v[6:7], off offset:2048
	v_add_co_u32_e32 v6, vcc, 0x65000, v4
	s_nop 1
	v_addc_co_u32_e32 v7, vcc, 0, v5, vcc
	global_load_dword v113, v[6:7], off offset:2048
	v_add_co_u32_e32 v6, vcc, 0xb000, v4
	s_nop 1
	v_addc_co_u32_e32 v7, vcc, 0, v5, vcc
	global_load_dword v114, v[6:7], off
	v_add_co_u32_e32 v6, vcc, 0x6b000, v4
	s_nop 1
	v_addc_co_u32_e32 v7, vcc, 0, v5, vcc
	global_load_dword v115, v[6:7], off
	v_add_co_u32_e32 v6, vcc, s12, v4
	s_mov_b32 s12, 0x16000
	s_nop 0
	v_addc_co_u32_e32 v7, vcc, 0, v5, vcc
	global_load_dword v116, v[6:7], off offset:2048
	v_add_co_u32_e32 v6, vcc, 0x70000, v4
	s_nop 1
	v_addc_co_u32_e32 v7, vcc, 0, v5, vcc
	global_load_dword v117, v[6:7], off offset:2048
	v_add_co_u32_e32 v6, vcc, s12, v4
	s_movk_i32 s12, 0x15ff
	s_nop 0
	v_addc_co_u32_e32 v7, vcc, 0, v5, vcc
	global_load_dword v118, v[6:7], off
	v_add_co_u32_e32 v6, vcc, 0x76000, v4
	s_nop 1
	v_addc_co_u32_e32 v7, vcc, 0, v5, vcc
	global_load_dword v119, v[6:7], off
	v_add_co_u32_e32 v6, vcc, 0x1b000, v4
	s_nop 1
	v_addc_co_u32_e32 v7, vcc, 0, v5, vcc
	global_load_dword v120, v[6:7], off offset:2048
	v_add_co_u32_e32 v6, vcc, 0x7b000, v4
	s_nop 1
	v_addc_co_u32_e32 v7, vcc, 0, v5, vcc
	global_load_dword v121, v[6:7], off offset:2048
	v_add_co_u32_e32 v6, vcc, 0x21000, v4
	s_nop 1
	v_addc_co_u32_e32 v7, vcc, 0, v5, vcc
	global_load_dword v122, v[6:7], off
	v_add_co_u32_e32 v6, vcc, 0x81000, v4
	s_nop 1
	v_addc_co_u32_e32 v7, vcc, 0, v5, vcc
	global_load_dword v123, v[6:7], off
	v_add_co_u32_e32 v6, vcc, 0x26000, v4
	s_nop 1
	v_addc_co_u32_e32 v7, vcc, 0, v5, vcc
	global_load_dword v124, v[6:7], off offset:2048
	v_add_co_u32_e32 v6, vcc, 0x86000, v4
	s_nop 1
	v_addc_co_u32_e32 v7, vcc, 0, v5, vcc
	global_load_dword v125, v[6:7], off offset:2048
	v_add_co_u32_e32 v6, vcc, 0x2c000, v4
	s_nop 1
	v_addc_co_u32_e32 v7, vcc, 0, v5, vcc
	global_load_dword v126, v[6:7], off
	v_add_co_u32_e32 v6, vcc, 0x8c000, v4
	s_nop 1
	v_addc_co_u32_e32 v7, vcc, 0, v5, vcc
	global_load_dword v127, v[6:7], off
	v_add_co_u32_e32 v6, vcc, 0x31000, v4
	s_nop 1
	v_addc_co_u32_e32 v7, vcc, 0, v5, vcc
	global_load_dword v128, v[6:7], off offset:2048
	v_add_co_u32_e32 v6, vcc, 0x91000, v4
	s_nop 1
	v_addc_co_u32_e32 v7, vcc, 0, v5, vcc
	global_load_dword v129, v[6:7], off offset:2048
	v_add_co_u32_e32 v6, vcc, 0x37000, v4
	s_nop 1
	v_addc_co_u32_e32 v7, vcc, 0, v5, vcc
	global_load_dword v130, v[6:7], off
	v_add_co_u32_e32 v6, vcc, 0x97000, v4
	s_nop 1
	v_addc_co_u32_e32 v7, vcc, 0, v5, vcc
	global_load_dword v131, v[6:7], off
	v_add_co_u32_e32 v6, vcc, 0x3c000, v4
	s_nop 1
	v_addc_co_u32_e32 v7, vcc, 0, v5, vcc
	global_load_dword v132, v[6:7], off offset:2048
	v_add_co_u32_e32 v6, vcc, 0x9c000, v4
	s_nop 1
	v_addc_co_u32_e32 v7, vcc, 0, v5, vcc
	global_load_dword v133, v[6:7], off offset:2048
	v_add_co_u32_e32 v6, vcc, 0x42000, v4
	s_nop 1
	v_addc_co_u32_e32 v7, vcc, 0, v5, vcc
	global_load_dword v134, v[6:7], off
	v_add_co_u32_e32 v6, vcc, 0xa2000, v4
	s_nop 1
	v_addc_co_u32_e32 v7, vcc, 0, v5, vcc
	global_load_dword v135, v[6:7], off
	v_add_co_u32_e32 v6, vcc, 0x47000, v4
	s_nop 1
	v_addc_co_u32_e32 v7, vcc, 0, v5, vcc
	global_load_dword v136, v[6:7], off offset:2048
	v_add_co_u32_e32 v6, vcc, 0xa7000, v4
	s_nop 1
	v_addc_co_u32_e32 v7, vcc, 0, v5, vcc
	global_load_dword v137, v[6:7], off offset:2048
	v_add_co_u32_e32 v6, vcc, 0x4d000, v4
	s_nop 1
	v_addc_co_u32_e32 v7, vcc, 0, v5, vcc
	global_load_dword v138, v[6:7], off
	v_add_co_u32_e32 v6, vcc, 0xad000, v4
	s_nop 1
	v_addc_co_u32_e32 v7, vcc, 0, v5, vcc
	global_load_dword v139, v[6:7], off
	v_add_co_u32_e32 v6, vcc, 0x52000, v4
	s_nop 1
	v_addc_co_u32_e32 v7, vcc, 0, v5, vcc
	global_load_dword v140, v[6:7], off offset:2048
	v_add_co_u32_e32 v6, vcc, 0xb2000, v4
	s_nop 1
	v_addc_co_u32_e32 v7, vcc, 0, v5, vcc
	global_load_dword v141, v[6:7], off offset:2048
	s_waitcnt vmcnt(0)
	v_add_f32_e32 v8, 0, v110
	v_add_f32_e32 v9, 0, v111
	v_add_f32_e32 v8, v8, v112
	v_add_f32_e32 v9, v9, v113
	v_add_f32_e32 v8, v8, v114
	v_add_f32_e32 v9, v9, v115
	v_add_f32_e32 v8, v8, v116
	v_add_f32_e32 v9, v9, v117
	v_add_f32_e32 v8, v8, v118
	v_add_f32_e32 v9, v9, v119
	v_add_f32_e32 v8, v8, v120
	v_add_f32_e32 v9, v9, v121
	v_add_f32_e32 v8, v8, v122
	v_add_f32_e32 v9, v9, v123
	v_add_f32_e32 v8, v8, v124
	v_add_f32_e32 v9, v9, v125
	v_add_f32_e32 v8, v8, v126
	v_add_f32_e32 v9, v9, v127
	v_add_f32_e32 v8, v8, v128
	v_add_f32_e32 v9, v9, v129
	v_add_f32_e32 v8, v8, v130
	v_add_f32_e32 v9, v9, v131
	v_add_f32_e32 v8, v8, v132
	v_add_f32_e32 v9, v9, v133
	v_add_f32_e32 v8, v8, v134
	v_add_f32_e32 v9, v9, v135
	v_add_f32_e32 v8, v8, v136
	v_add_f32_e32 v9, v9, v137
	v_add_f32_e32 v8, v8, v138
	v_add_f32_e32 v9, v9, v139
	v_add_f32_e32 v8, v8, v140
	v_add_f32_e32 v9, v9, v141
	v_add_co_u32_e32 v6, vcc, 0xc0000, v4
	s_nop 1
	v_addc_co_u32_e32 v7, vcc, 0, v5, vcc
	global_store_dword v[6:7], v8, off
	v_add_co_u32_e32 v6, vcc, 0xc8000, v4
	s_nop 1
	v_addc_co_u32_e32 v7, vcc, 0, v5, vcc
	v_cmp_lt_i32_e32 vcc, s12, v3
	v_lshl_add_u64 v[4:5], v[4:5], 0, s[24:25]
	s_or_b64 s[26:27], vcc, s[26:27]
	global_store_dword v[6:7], v9, off
	s_andn2_b64 exec, exec, s[26:27]
	s_cbranch_execnz .LBB0_1235

; #define LAS __attribute__((address_space(3)))
; DI float silu_f(float x) { return x * __builtin_amdgcn_rcpf(1.0f + __expf(-x)); }
; DI u32x4 pack8(const float (&v)[8]) { u32x4 w; w.x = pk2(v[0], v[1]); w.y = pk2(v[2], v[3]); w.z = pk2(v[4], v[5]); w.w = pk2(v[6], v[7]); return w; }
; DI void conv_load(const bf16_t* src, int s0, u32x4 (&raw)[7]) {
; #pragma unroll
;     for (int i = 0; i < 7; ++i) { const int s = s0 - 3 + i; raw[i] = (s >= 0) ? *(const u32x4*)(src + (size_t)s * HP) : (u32x4){0u, 0u, 0u, 0u}; }
; }
; template <bool SILU>
; DI void conv_compute(const u32x4 (&raw)[7], const float* w, int C, const float* bias, float (&out)[4][8]) {
;     float wv[4][8], bv[8], x[7][8];
; #pragma unroll
;     for (int j = 0; j < 4; ++j) { const f32x4 a = *(const f32x4*)(w + (size_t)j * C), b = *(const f32x4*)(w + (size_t)j * C + 4);
;         wv[j][0] = a[0]; wv[j][1] = a[1]; wv[j][2] = a[2]; wv[j][3] = a[3]; wv[j][4] = b[0]; wv[j][5] = b[1]; wv[j][6] = b[2]; wv[j][7] = b[3]; }
;     { const f32x4 a = *(const f32x4*)bias, b = *(const f32x4*)(bias + 4); bv[0] = a[0]; bv[1] = a[1]; bv[2] = a[2]; bv[3] = a[3]; bv[4] = b[0]; bv[5] = b[1]; bv[6] = b[2]; bv[7] = b[3]; }
; #pragma unroll
;     for (int i = 0; i < 7; ++i) unpack8(raw[i], x[i]);
; #pragma unroll
;     for (int t = 0; t < 4; ++t)
; #pragma unroll
;         for (int c = 0; c < 8; ++c) { float v = bv[c] + wv[0][c] * x[t][c] + wv[1][c] * x[t + 1][c] + wv[2][c] * x[t + 2][c] + wv[3][c] * x[t + 3][c]; out[t][c] = SILU ? silu_f(v) : v; }
; }
; DI void ssd_pass2(LAS unsigned char* lds, const Args& a, const LayerP& P, int unit, int wv) {
;     ...
;         { float o[4][8]; conv8x4<true>(Hb + C_XBC + 512 + g * 128 + cv * 8, c * 128 + t0, P.ssd_cw + 512 + g * 128 + cv * 8, 768, P.ssd_cb + 512 + g * 128 + cv * 8, o);
; #pragma unroll
;           for (int t = 0; t < 4; ++t) *(LAS u32x4*)(Cm + (t0 + t) * PT + cv * 8) = pack8(o[t]); }
.LBB0_1387:
	s_or_b64 exec, exec, s[2:3]
	s_lshl_b64 s[2:3], s[58:59], 2
	v_lshlrev_b32_e32 v122, 3, v120
	s_add_u32 s36, s40, s2
	s_addc_u32 s37, s41, s3
	v_lshlrev_b32_e32 v0, 2, v122
	v_lshl_add_u64 v[102:103], s[36:37], 0, v[0:1]
	s_mov_b64 s[94:95], 0x800
	v_lshl_add_u64 v[14:15], v[102:103], 0, s[94:95]
	s_add_u32 s94, s42, s2
	s_addc_u32 s95, s43, s3
	s_mov_b64 s[2:3], 0x2000
	global_load_dwordx4 v[6:9], v0, s[36:37] offset:2064
	global_load_dwordx4 v[30:33], v0, s[36:37] offset:2048
	global_load_dwordx4 v[10:13], v[14:15], off offset:3088
	global_load_dwordx4 v[36:39], v[14:15], off offset:3072
	v_lshl_add_u64 v[14:15], v[102:103], 0, s[2:3]
	s_movk_i32 s2, 0x2000
	v_add_co_u32_e32 v104, vcc, s2, v102
	s_mov_b64 s[2:3], 0x2c00
	s_nop 0
	v_addc_co_u32_e32 v105, vcc, 0, v103, vcc
	v_lshl_add_u64 v[18:19], v[102:103], 0, s[2:3]
	global_load_dwordx4 v[40:43], v[104:105], off
	s_nop 0
	global_load_dwordx4 v[14:17], v[14:15], off offset:16
	s_nop 0
	global_load_dwordx4 v[44:47], v[104:105], off offset:3072
	s_nop 0
	global_load_dwordx4 v[18:21], v[18:19], off offset:16
	s_nop 0
	global_load_dwordx4 v[22:25], v0, s[94:95] offset:2064
	global_load_dwordx4 v[48:51], v0, s[94:95] offset:2048
	s_waitcnt vmcnt(10)
	v_lshlrev_b32_e32 v72, 16, v60
	v_and_b32_e32 v73, 0xffff0000, v60
	v_lshlrev_b32_e32 v82, 16, v56
	v_and_b32_e32 v83, 0xffff0000, v56
	v_lshlrev_b32_e32 v76, 16, v68
	v_and_b32_e32 v77, 0xffff0000, v68
	v_lshlrev_b32_e32 v74, 16, v64
	v_and_b32_e32 v75, 0xffff0000, v64
	v_lshlrev_b32_e32 v80, 16, v61
	v_and_b32_e32 v81, 0xffff0000, v61
	v_lshlrev_b32_e32 v84, 16, v57
	v_and_b32_e32 v85, 0xffff0000, v57
	v_lshlrev_b32_e32 v60, 16, v65
	v_and_b32_e32 v61, 0xffff0000, v65
	v_lshlrev_b32_e32 v86, 16, v58
	v_and_b32_e32 v87, 0xffff0000, v58
	v_lshlrev_b32_e32 v68, 16, v66
	v_lshlrev_b32_e32 v92, 16, v59
	v_and_b32_e32 v93, 0xffff0000, v59
	v_and_b32_e32 v59, 0xffff0000, v67
	v_lshlrev_b32_e32 v90, 16, v54
	v_and_b32_e32 v91, 0xffff0000, v54
	s_lshl_b32 s58, s15, 1
	s_or_b32 s2, s58, s12
	s_ashr_i32 s3, s2, 31
	s_lshl_b64 s[2:3], s[2:3], 14
	s_add_u32 s2, s46, s2
	s_addc_u32 s3, s47, s3
	s_waitcnt vmcnt(0)
	v_pk_fma_f32 v[72:73], v[30:31], v[72:73], v[48:49]
	s_nop 0
	v_pk_fma_f32 v[72:73], v[36:37], v[82:83], v[72:73]
	s_nop 0
	v_pk_fma_f32 v[72:73], v[40:41], v[76:77], v[72:73]
	s_nop 0
	v_pk_fma_f32 v[72:73], v[44:45], v[74:75], v[72:73]
	s_nop 0
	v_mul_f32_e32 v56, 0xbfb8aa3b, v72
	v_exp_f32_e32 v56, v56
	s_nop 0
	v_add_f32_e32 v56, 1.0, v56
	v_rcp_f32_e32 v78, v56
	v_mul_f32_e32 v56, 0xbfb8aa3b, v73
	v_exp_f32_e32 v56, v56
	s_nop 0
	v_add_f32_e32 v56, 1.0, v56
	v_rcp_f32_e32 v79, v56
	v_pk_fma_f32 v[56:57], v[32:33], v[80:81], v[50:51]
	v_lshlrev_b32_e32 v80, 16, v70
	v_pk_fma_f32 v[56:57], v[38:39], v[84:85], v[56:57]
	v_pk_mul_f32 v[72:73], v[72:73], v[78:79]
	v_lshlrev_b32_e32 v78, 16, v69
	v_and_b32_e32 v79, 0xffff0000, v69
	v_pk_fma_f32 v[56:57], v[42:43], v[78:79], v[56:57]
	v_and_b32_e32 v81, 0xffff0000, v70
	v_pk_fma_f32 v[56:57], v[46:47], v[60:61], v[56:57]
	v_and_b32_e32 v69, 0xffff0000, v66
	v_mul_f32_e32 v64, 0xbfb8aa3b, v56
	v_mul_f32_e32 v65, 0xbfb8aa3b, v57
	v_exp_f32_e32 v64, v64
	v_exp_f32_e32 v65, v65
	v_add_f32_e32 v64, 1.0, v64
	v_add_f32_e32 v65, 1.0, v65
	v_rcp_f32_e32 v64, v64
	v_rcp_f32_e32 v65, v65
	s_nop 0
	v_pk_mul_f32 v[56:57], v[56:57], v[64:65]
	v_lshlrev_b32_e32 v64, 16, v62
	v_and_b32_e32 v65, 0xffff0000, v62
	v_pk_fma_f32 v[64:65], v[6:7], v[64:65], v[22:23]
	v_lshlrev_b32_e32 v62, 16, v71
	v_pk_fma_f32 v[64:65], v[10:11], v[86:87], v[64:65]
	s_nop 0
	v_pk_fma_f32 v[64:65], v[14:15], v[80:81], v[64:65]
	s_nop 0
	v_pk_fma_f32 v[64:65], v[18:19], v[68:69], v[64:65]
	s_nop 0
	v_mul_f32_e32 v58, 0xbfb8aa3b, v64
	v_exp_f32_e32 v58, v58
	s_nop 0
	v_add_f32_e32 v58, 1.0, v58
	v_rcp_f32_e32 v88, v58
	v_mul_f32_e32 v58, 0xbfb8aa3b, v65
	v_exp_f32_e32 v58, v58
	s_nop 0
	v_add_f32_e32 v58, 1.0, v58
	v_rcp_f32_e32 v89, v58
	v_lshlrev_b32_e32 v58, 16, v67
	v_pk_mul_f32 v[64:65], v[64:65], v[88:89]
	v_lshlrev_b32_e32 v88, 16, v63
	v_and_b32_e32 v89, 0xffff0000, v63
	v_pk_fma_f32 v[66:67], v[8:9], v[88:89], v[24:25]
	v_and_b32_e32 v63, 0xffff0000, v71
	v_pk_fma_f32 v[66:67], v[12:13], v[92:93], v[66:67]
	v_lshlrev_b32_e32 v88, 16, v52
	v_pk_fma_f32 v[66:67], v[16:17], v[62:63], v[66:67]
	v_and_b32_e32 v89, 0xffff0000, v52
	v_pk_fma_f32 v[66:67], v[20:21], v[58:59], v[66:67]
	s_nop 0
	v_mul_f32_e32 v70, 0xbfb8aa3b, v66
	v_mul_f32_e32 v71, 0xbfb8aa3b, v67
	v_exp_f32_e32 v70, v70
	v_exp_f32_e32 v71, v71
	v_add_f32_e32 v70, 1.0, v70
	v_add_f32_e32 v71, 1.0, v71
	v_rcp_f32_e32 v70, v70
	v_rcp_f32_e32 v71, v71
	s_nop 0
	v_pk_mul_f32 v[66:67], v[66:67], v[70:71]
	v_pk_fma_f32 v[70:71], v[30:31], v[82:83], v[48:49]
	s_nop 0
	v_pk_fma_f32 v[70:71], v[36:37], v[76:77], v[70:71]
	v_pk_fma_f32 v[76:77], v[30:31], v[76:77], v[48:49]
	v_pk_fma_f32 v[70:71], v[40:41], v[74:75], v[70:71]
	v_pk_fma_f32 v[76:77], v[36:37], v[74:75], v[76:77]
	v_pk_fma_f32 v[70:71], v[44:45], v[88:89], v[70:71]
	v_pk_fma_f32 v[76:77], v[40:41], v[88:89], v[76:77]
	v_mul_f32_e32 v52, 0xbfb8aa3b, v70
	v_exp_f32_e32 v52, v52
	v_pk_fma_f32 v[30:31], v[30:31], v[74:75], v[48:49]
	v_add_f32_e32 v52, 1.0, v52
	v_rcp_f32_e32 v82, v52
	v_mul_f32_e32 v52, 0xbfb8aa3b, v71
	v_exp_f32_e32 v52, v52
	v_pk_fma_f32 v[30:31], v[36:37], v[88:89], v[30:31]
	v_add_f32_e32 v52, 1.0, v52
	v_rcp_f32_e32 v83, v52
	s_nop 0
	v_pk_mul_f32 v[70:71], v[70:71], v[82:83]
	v_lshlrev_b32_e32 v82, 16, v53
	v_and_b32_e32 v83, 0xffff0000, v53
	v_pk_fma_f32 v[52:53], v[32:33], v[84:85], v[50:51]
	s_nop 0
	v_pk_fma_f32 v[52:53], v[38:39], v[78:79], v[52:53]
; #define LAS __attribute__((address_space(3)))
; DI float silu_f(float x) { return x * __builtin_amdgcn_rcpf(1.0f + __expf(-x)); }
; DI u32x4 pack8(const float (&v)[8]) { u32x4 w; w.x = pk2(v[0], v[1]); w.y = pk2(v[2], v[3]); w.z = pk2(v[4], v[5]); w.w = pk2(v[6], v[7]); return w; }
; template <bool SILU>
; DI void conv_compute(const u32x4 (&raw)[7], const float* w, int C, const float* bias, float (&out)[4][8]) {
;     float wv[4][8], bv[8], x[7][8];
; #pragma unroll
;     for (int j = 0; j < 4; ++j) { const f32x4 a = *(const f32x4*)(w + (size_t)j * C), b = *(const f32x4*)(w + (size_t)j * C + 4);
;         wv[j][0] = a[0]; wv[j][1] = a[1]; wv[j][2] = a[2]; wv[j][3] = a[3]; wv[j][4] = b[0]; wv[j][5] = b[1]; wv[j][6] = b[2]; wv[j][7] = b[3]; }
;     { const f32x4 a = *(const f32x4*)bias, b = *(const f32x4*)(bias + 4); bv[0] = a[0]; bv[1] = a[1]; bv[2] = a[2]; bv[3] = a[3]; bv[4] = b[0]; bv[5] = b[1]; bv[6] = b[2]; bv[7] = b[3]; }
; #pragma unroll
;     for (int i = 0; i < 7; ++i) unpack8(raw[i], x[i]);
; #pragma unroll
;     for (int t = 0; t < 4; ++t)
; #pragma unroll
;         for (int c = 0; c < 8; ++c) { float v = bv[c] + wv[0][c] * x[t][c] + wv[1][c] * x[t + 1][c] + wv[2][c] * x[t + 2][c] + wv[3][c] * x[t + 3][c]; out[t][c] = SILU ? silu_f(v) : v; }
; }
; DI void ssd_pass2(LAS unsigned char* lds, const Args& a, const LayerP& P, int unit, int wv) {
;     ...
;         { float o[4][8]; conv8x4<true>(Hb + C_XBC + 512 + g * 128 + cv * 8, c * 128 + t0, P.ssd_cw + 512 + g * 128 + cv * 8, 768, P.ssd_cb + 512 + g * 128 + cv * 8, o);
; #pragma unroll
;           for (int t = 0; t < 4; ++t) *(LAS u32x4*)(Cm + (t0 + t) * PT + cv * 8) = pack8(o[t]); }
;         { const bf16_t* ST = (const bf16_t*)((const unsigned char*)a.out + DO_ST) + ((size_t)((b * NCH + c) * 4 + 2 * g)) * 8192;
; #pragma unroll
;           for (int i = 0; i < 4; ++i) { const int e8 = (i * 512 + tid) * 8; *(LAS u32x4*)(R1 + (e8 >> 7) * PT + (e8 & 127)) = *(const u32x4*)(ST + e8); } }
	v_pk_fma_f32 v[78:79], v[32:33], v[78:79], v[50:51]
	v_pk_fma_f32 v[52:53], v[42:43], v[60:61], v[52:53]
	v_pk_fma_f32 v[78:79], v[38:39], v[60:61], v[78:79]
	v_pk_fma_f32 v[52:53], v[46:47], v[82:83], v[52:53]
	v_pk_fma_f32 v[78:79], v[42:43], v[82:83], v[78:79]
	v_mul_f32_e32 v84, 0xbfb8aa3b, v52
	v_mul_f32_e32 v85, 0xbfb8aa3b, v53
	v_exp_f32_e32 v84, v84
	v_exp_f32_e32 v85, v85
	v_pk_fma_f32 v[32:33], v[32:33], v[60:61], v[50:51]
	v_add_f32_e32 v84, 1.0, v84
	v_add_f32_e32 v85, 1.0, v85
	v_rcp_f32_e32 v84, v84
	v_rcp_f32_e32 v85, v85
	v_pk_fma_f32 v[32:33], v[38:39], v[82:83], v[32:33]
	v_pk_mul_f32 v[52:53], v[52:53], v[84:85]
	v_pk_fma_f32 v[84:85], v[6:7], v[86:87], v[22:23]
	s_nop 0
	v_pk_fma_f32 v[84:85], v[10:11], v[80:81], v[84:85]
	v_pk_fma_f32 v[80:81], v[6:7], v[80:81], v[22:23]
	v_pk_fma_f32 v[84:85], v[14:15], v[68:69], v[84:85]
	v_pk_fma_f32 v[80:81], v[10:11], v[68:69], v[80:81]
	v_pk_fma_f32 v[84:85], v[18:19], v[90:91], v[84:85]
	v_pk_fma_f32 v[80:81], v[14:15], v[90:91], v[80:81]
	v_mul_f32_e32 v54, 0xbfb8aa3b, v84
	v_exp_f32_e32 v54, v54
	v_pk_fma_f32 v[6:7], v[6:7], v[68:69], v[22:23]
	v_add_f32_e32 v54, 1.0, v54
	v_rcp_f32_e32 v86, v54
	v_mul_f32_e32 v54, 0xbfb8aa3b, v85
	v_exp_f32_e32 v54, v54
	v_pk_fma_f32 v[6:7], v[10:11], v[90:91], v[6:7]
	v_lshl_add_u32 v10, v122, 1, 0
	v_mul_lo_u32 v11, v121, s56
	v_add_f32_e32 v54, 1.0, v54
	v_rcp_f32_e32 v87, v54
	v_lshlrev_b32_e32 v54, 16, v55
	v_and_b32_e32 v55, 0xffff0000, v55
	v_add_u32_e32 v132, v10, v11
	v_pk_mul_f32 v[84:85], v[84:85], v[86:87]
	v_pk_fma_f32 v[86:87], v[8:9], v[92:93], v[24:25]
	s_nop 0
	v_pk_fma_f32 v[86:87], v[12:13], v[62:63], v[86:87]
	v_pk_fma_f32 v[62:63], v[8:9], v[62:63], v[24:25]
	v_pk_fma_f32 v[86:87], v[16:17], v[58:59], v[86:87]
	v_pk_fma_f32 v[62:63], v[12:13], v[58:59], v[62:63]
	v_pk_fma_f32 v[86:87], v[20:21], v[54:55], v[86:87]
	v_pk_fma_f32 v[62:63], v[16:17], v[54:55], v[62:63]
	v_mul_f32_e32 v92, 0xbfb8aa3b, v86
	v_mul_f32_e32 v93, 0xbfb8aa3b, v87
	v_exp_f32_e32 v92, v92
	v_exp_f32_e32 v93, v93
	v_add_f32_e32 v92, 1.0, v92
	v_add_f32_e32 v93, 1.0, v93
	v_rcp_f32_e32 v92, v92
	v_rcp_f32_e32 v93, v93
	s_nop 0
	v_pk_mul_f32 v[86:87], v[86:87], v[92:93]
	v_lshlrev_b32_e32 v92, 16, v26
	v_and_b32_e32 v93, 0xffff0000, v26
	v_pk_fma_f32 v[76:77], v[44:45], v[92:93], v[76:77]
	v_pk_fma_f32 v[30:31], v[40:41], v[92:93], v[30:31]
	v_mul_f32_e32 v26, 0xbfb8aa3b, v76
	v_exp_f32_e32 v26, v26
	s_nop 0
	v_add_f32_e32 v26, 1.0, v26
	v_rcp_f32_e32 v96, v26
	v_mul_f32_e32 v26, 0xbfb8aa3b, v77
	v_exp_f32_e32 v26, v26
	s_nop 0
	v_add_f32_e32 v26, 1.0, v26
	v_rcp_f32_e32 v97, v26
	v_lshlrev_b32_e32 v26, 16, v27
	v_and_b32_e32 v27, 0xffff0000, v27
	v_pk_fma_f32 v[78:79], v[46:47], v[26:27], v[78:79]
	v_pk_mul_f32 v[76:77], v[76:77], v[96:97]
	v_mul_f32_e32 v95, 0xbfb8aa3b, v78
	v_exp_f32_e32 v95, v95
	v_pk_fma_f32 v[26:27], v[42:43], v[26:27], v[32:33]
	v_add_f32_e32 v95, 1.0, v95
	v_rcp_f32_e32 v96, v95
	v_mul_f32_e32 v95, 0xbfb8aa3b, v79
	v_exp_f32_e32 v95, v95
	s_nop 0
	v_add_f32_e32 v95, 1.0, v95
	v_rcp_f32_e32 v97, v95
	s_nop 0
	v_pk_mul_f32 v[78:79], v[78:79], v[96:97]
	v_lshlrev_b32_e32 v96, 16, v28
	v_and_b32_e32 v97, 0xffff0000, v28
	v_pk_fma_f32 v[80:81], v[18:19], v[96:97], v[80:81]
	v_pk_fma_f32 v[6:7], v[14:15], v[96:97], v[6:7]
	v_mul_f32_e32 v28, 0xbfb8aa3b, v80
	v_exp_f32_e32 v28, v28
	s_nop 0
	v_add_f32_e32 v28, 1.0, v28
	v_rcp_f32_e32 v98, v28
	v_mul_f32_e32 v28, 0xbfb8aa3b, v81
	v_exp_f32_e32 v28, v28
	s_nop 0
	v_add_f32_e32 v28, 1.0, v28
	v_rcp_f32_e32 v99, v28
	v_lshlrev_b32_e32 v28, 16, v29
	v_and_b32_e32 v29, 0xffff0000, v29
	v_pk_fma_f32 v[62:63], v[20:21], v[28:29], v[62:63]
	v_pk_mul_f32 v[80:81], v[80:81], v[98:99]
	v_mul_f32_e32 v95, 0xbfb8aa3b, v62
	v_exp_f32_e32 v95, v95
	s_nop 0
	v_add_f32_e32 v95, 1.0, v95
	v_rcp_f32_e32 v98, v95
	v_mul_f32_e32 v95, 0xbfb8aa3b, v63
	v_exp_f32_e32 v95, v95
	s_nop 0
	v_add_f32_e32 v95, 1.0, v95
	v_rcp_f32_e32 v99, v95
	s_nop 0
	v_pk_mul_f32 v[62:63], v[62:63], v[98:99]
	v_lshlrev_b32_e32 v98, 16, v2
	v_and_b32_e32 v99, 0xffff0000, v2
	v_pk_fma_f32 v[30:31], v[44:45], v[98:99], v[30:31]
	s_nop 0
	v_mul_f32_e32 v2, 0xbfb8aa3b, v30
	v_exp_f32_e32 v2, v2
	s_nop 0
	v_add_f32_e32 v2, 1.0, v2
	v_rcp_f32_e32 v36, v2
	v_mul_f32_e32 v2, 0xbfb8aa3b, v31
	v_exp_f32_e32 v2, v2
	s_nop 0
	v_add_f32_e32 v2, 1.0, v2
	v_rcp_f32_e32 v37, v2
	v_lshlrev_b32_e32 v2, 16, v3
	v_and_b32_e32 v3, 0xffff0000, v3
	v_pk_fma_f32 v[2:3], v[46:47], v[2:3], v[26:27]
	v_pk_mul_f32 v[30:31], v[30:31], v[36:37]
	v_mul_f32_e32 v26, 0xbfb8aa3b, v2
	v_mul_f32_e32 v27, 0xbfb8aa3b, v3
	v_exp_f32_e32 v26, v26
	v_exp_f32_e32 v27, v27
	v_mov_b32_e32 v36, 0
	v_mov_b32_e32 v37, 0
	v_add_f32_e32 v26, 1.0, v26
	v_add_f32_e32 v27, 1.0, v27
	v_rcp_f32_e32 v26, v26
	v_rcp_f32_e32 v27, v27
	s_nop 0
	v_pk_mul_f32 v[26:27], v[2:3], v[26:27]
	v_lshlrev_b32_e32 v2, 16, v4
	v_and_b32_e32 v3, 0xffff0000, v4
	v_pk_fma_f32 v[2:3], v[18:19], v[2:3], v[6:7]
	s_nop 0
	v_mul_f32_e32 v4, 0xbfb8aa3b, v2
	v_exp_f32_e32 v4, v4
	s_nop 0
	v_add_f32_e32 v4, 1.0, v4
	v_rcp_f32_e32 v6, v4
	v_mul_f32_e32 v4, 0xbfb8aa3b, v3
	v_exp_f32_e32 v4, v4
	s_nop 0
	v_add_f32_e32 v4, 1.0, v4
	v_rcp_f32_e32 v7, v4
	s_nop 0
	v_pk_mul_f32 v[6:7], v[2:3], v[6:7]
	v_lshlrev_b32_e32 v2, 16, v5
	v_and_b32_e32 v3, 0xffff0000, v5
	v_pk_fma_f32 v[4:5], v[8:9], v[58:59], v[24:25]
	s_nop 0
	v_pk_fma_f32 v[4:5], v[12:13], v[54:55], v[4:5]
	s_nop 0
	v_pk_fma_f32 v[4:5], v[16:17], v[28:29], v[4:5]
	s_nop 0
	v_pk_fma_f32 v[2:3], v[20:21], v[2:3], v[4:5]
	s_nop 0
	v_mul_f32_e32 v4, 0xbfb8aa3b, v2
	v_mul_f32_e32 v5, 0xbfb8aa3b, v3
	v_exp_f32_e32 v4, v4
	v_exp_f32_e32 v5, v5
	v_add_f32_e32 v4, 1.0, v4
	v_add_f32_e32 v5, 1.0, v5
	v_rcp_f32_e32 v4, v4
	v_rcp_f32_e32 v5, v5
	s_nop 0
	v_pk_mul_f32 v[8:9], v[2:3], v[4:5]
	v_cvt_pk_bf16_f32 v2, v72, v73
	v_cvt_pk_bf16_f32 v3, v56, v57
	v_cvt_pk_bf16_f32 v4, v64, v65
	v_cvt_pk_bf16_f32 v5, v66, v67
	ds_write_b128 v132, v[2:5]
	v_cvt_pk_bf16_f32 v2, v70, v71
	v_cvt_pk_bf16_f32 v3, v52, v53
	v_cvt_pk_bf16_f32 v4, v84, v85
	v_cvt_pk_bf16_f32 v5, v86, v87
	ds_write_b128 v132, v[2:5] offset:272
	v_cvt_pk_bf16_f32 v2, v76, v77
	v_cvt_pk_bf16_f32 v3, v78, v79
	v_cvt_pk_bf16_f32 v4, v80, v81
	v_cvt_pk_bf16_f32 v5, v62, v63
	ds_write_b128 v132, v[2:5] offset:544
	v_cvt_pk_bf16_f32 v4, v6, v7
	v_or_b32_e32 v6, 3, v94
	v_mul_lo_u32 v6, v6, s56
	v_cvt_pk_bf16_f32 v2, v30, v31
	v_cvt_pk_bf16_f32 v3, v26, v27
	v_cvt_pk_bf16_f32 v5, v8, v9
	v_add_u32_e32 v133, v10, v6
	ds_write_b128 v133, v[2:5]
	v_lshlrev_b32_e32 v150, 4, v35
	global_load_dwordx4 v[134:137], v150, s[2:3]
	s_add_u32 s2, s2, 0x2000
	s_addc_u32 s3, s3, 0
	global_load_dwordx4 v[138:141], v150, s[2:3]
	s_add_u32 s2, s2, 0x2000
	s_addc_u32 s3, s3, 0
	global_load_dwordx4 v[142:145], v150, s[2:3]
	s_add_u32 s2, s2, 0x2000
	s_addc_u32 s3, s3, 0
	global_load_dwordx4 v[146:149], v150, s[2:3]
	v_and_b32_e32 v6, 0xf0, v150
	v_bfe_i32 v7, v35, 4, 25
	v_mad_u32_u24 v151, v7, s56, v6
	v_mov_b32_e32 v35, 0
	s_waitcnt vmcnt(3)
; #define LAS __attribute__((address_space(3)))
; DI void ssd_pass2(LAS unsigned char* lds, const Args& a, const LayerP& P, int unit, int wv) {
;     ...
;         { const bf16_t* ST = (const bf16_t*)((const unsigned char*)a.out + DO_ST) + ((size_t)((b * NCH + c) * 4 + 2 * g)) * 8192;
; #pragma unroll
;           for (int i = 0; i < 4; ++i) { const int e8 = (i * 512 + tid) * 8; *(LAS u32x4*)(R1 + (e8 >> 7) * PT + (e8 & 127)) = *(const u32x4*)(ST + e8); } }
;         u32x4 rawB[7]; conv_load(Hb + C_XBC + 256 + g * 128 + cv * 8, c * 128 + t0, rawB);
	ds_write_b128 v151, v[134:137] offset:34816
	s_waitcnt vmcnt(2)
	ds_write_b128 v151, v[138:141] offset:43520
	s_waitcnt vmcnt(1)
	ds_write_b128 v151, v[142:145] offset:52224
	s_waitcnt vmcnt(0)
	ds_write_b128 v151, v[146:149] offset:60928
	s_and_saveexec_b64 s[2:3], s[16:17]
	s_cbranch_execz .LBB0_1389
	v_mad_u64_u32 v[2:3], s[36:37], v126, s73, v[106:107]
	global_load_dwordx4 v[34:37], v[2:3], off offset:1824
